# prompt MLA loop head: first 8 K-fragment LDS reads issued right after the barrier, ahead of the next-tile DMA / V-load issue block (issue work hidden under the LDS latency)
# speedup vs baseline: 1.0072x; 1.0004x over previous
.LBB0_556:
	s_cmp_ge_u32 s58, s27
	s_waitcnt vmcnt(0)
	ds_write2_b64 v192, v[168:169], v[170:171] offset1:1
	ds_write2_b64 v193, v[164:165], v[166:167] offset1:1
	s_waitcnt lgkmcnt(0)
	s_barrier
	ds_read_b128 v[196:199], v188
	ds_read_b128 v[202:205], v188 offset:32
	ds_read_b128 v[206:209], v188 offset:64
	ds_read_b128 v[210:213], v188 offset:96
	ds_read_b128 v[220:223], v188 offset:128
	ds_read_b128 v[224:227], v188 offset:160
	ds_read_b128 v[2:5], v188 offset:192
	ds_read_b128 v[6:9], v188 offset:224
	s_cbranch_scc1 .LBB0_566
	v_readfirstlane_b32 s12, v152
	v_readfirstlane_b32 s13, v153
	v_readlane_b32 s22, v253, 29
	s_nop 3
	s_mul_i32 s23, s22, 0x140
	s_add_u32 s12, s12, s23
	s_addc_u32 s13, s13, 0
	s_xor_b32 s23, s98, 0x10000
	s_add_i32 s23, s23, s99
	s_mov_b32 m0, s23
	s_nop 0
	global_load_lds_dwordx4 v154, s[12:13]
	s_add_i32 m0, s23, 0x2000
	s_nop 0
	global_load_lds_dwordx4 v155, s[12:13]
	s_cmp_ge_u32 s99, 0x1400
	s_cbranch_scc1 .Lkdma_skip
	s_add_i32 m0, s23, 0x4000
	s_nop 0
	global_load_lds_dwordx4 v156, s[12:13]
.Lkdma_skip:
	v_readlane_b32 s12, v253, 29
	v_readlane_b32 s13, v253, 30
	s_lshl_b64 s[12:13], s[12:13], 1
	s_nop 0
	v_lshl_add_u64 v[158:159], v[172:173], 0, s[12:13]
	v_lshl_add_u64 v[160:161], v[174:175], 0, s[12:13]
	global_load_dwordx4 v[168:171], v[158:159], off
	global_load_dwordx4 v[164:167], v[160:161], off
.LBB0_566:
	s_and_saveexec_b64 s[22:23], vcc
	s_cbranch_execz .LBB0_555
	s_waitcnt lgkmcnt(7)
	v_mfma_f32_32x32x16_bf16 v[96:111], v[196:199], v[148:151], 0
	ds_read_b128 v[196:199], v188 offset:256
	s_waitcnt lgkmcnt(7)
	v_mfma_f32_32x32x16_bf16 v[96:111], v[202:205], v[144:147], v[96:111]
	ds_read_b128 v[202:205], v188 offset:288
	s_waitcnt lgkmcnt(7)
	v_mfma_f32_32x32x16_bf16 v[96:111], v[206:209], v[140:143], v[96:111]
	ds_read_b128 v[206:209], v188 offset:10752
	s_waitcnt lgkmcnt(7)
	v_mfma_f32_32x32x16_bf16 v[96:111], v[210:213], v[136:139], v[96:111]
	ds_read_b128 v[210:213], v188 offset:10784
	s_waitcnt lgkmcnt(7)
	v_mfma_f32_32x32x16_bf16 v[96:111], v[220:223], v[132:135], v[96:111]
	ds_read_b128 v[220:223], v188 offset:10816
	s_waitcnt lgkmcnt(7)
	v_mfma_f32_32x32x16_bf16 v[96:111], v[224:227], v[128:131], v[96:111]
	ds_read_b128 v[224:227], v188 offset:10848
	s_waitcnt lgkmcnt(7)
	v_mfma_f32_32x32x16_bf16 v[96:111], v[2:5], v[124:127], v[96:111]
	ds_read_b128 v[2:5], v188 offset:10880
	s_waitcnt lgkmcnt(7)
	v_mfma_f32_32x32x16_bf16 v[96:111], v[6:9], v[120:123], v[96:111]
	ds_read_b128 v[6:9], v188 offset:10912
	s_waitcnt lgkmcnt(7)
	v_mfma_f32_32x32x16_bf16 v[96:111], v[196:199], v[116:119], v[96:111]
	ds_read_b128 v[196:199], v188 offset:10944
	s_waitcnt lgkmcnt(7)
	v_mfma_f32_32x32x16_bf16 v[96:111], v[202:205], v[112:115], v[96:111]
	ds_read_b128 v[202:205], v188 offset:10976
	s_waitcnt lgkmcnt(7)
	v_mfma_f32_32x32x16_bf16 v[80:95], v[206:209], v[148:151], 0
	ds_read_b128 v[206:209], v188 offset:11008
	s_waitcnt lgkmcnt(7)
	v_mfma_f32_32x32x16_bf16 v[80:95], v[210:213], v[144:147], v[80:95]
	ds_read_b128 v[210:213], v188 offset:11040
	s_waitcnt lgkmcnt(7)
	v_mfma_f32_32x32x16_bf16 v[80:95], v[220:223], v[140:143], v[80:95]
	s_waitcnt lgkmcnt(6)
	v_mfma_f32_32x32x16_bf16 v[80:95], v[224:227], v[136:139], v[80:95]
	s_waitcnt lgkmcnt(5)
	v_mfma_f32_32x32x16_bf16 v[80:95], v[2:5], v[132:135], v[80:95]
	s_waitcnt lgkmcnt(4)
	v_mfma_f32_32x32x16_bf16 v[80:95], v[6:9], v[128:131], v[80:95]
	s_waitcnt lgkmcnt(3)
	v_mfma_f32_32x32x16_bf16 v[80:95], v[196:199], v[124:127], v[80:95]
	v_max_f32_e32 v0, v97, v97
	v_max_f32_e32 v10, v96, v96
	v_max_f32_e32 v0, v10, v0
	v_max3_f32 v0, v0, v98, v99
	v_max3_f32 v0, v0, v100, v101
	v_max3_f32 v0, v0, v102, v103
	v_max3_f32 v0, v0, v104, v105
	v_max3_f32 v0, v0, v106, v107
	v_max3_f32 v0, v0, v108, v109
	v_max3_f32 v0, v0, v110, v111
	v_and_b32_e32 v3, 64, v218
	v_xor_b32_e32 v2, 32, v218
	v_add_u32_e32 v3, 64, v3
	v_cmp_lt_i32_e64 s[12:13], v2, v3
	s_nop 1
	v_cndmask_b32_e64 v2, v218, v2, s[12:13]
	s_waitcnt lgkmcnt(2)
	v_mfma_f32_32x32x16_bf16 v[80:95], v[202:205], v[120:123], v[80:95]
	s_waitcnt lgkmcnt(1)
	v_mfma_f32_32x32x16_bf16 v[80:95], v[206:209], v[116:119], v[80:95]
	s_waitcnt lgkmcnt(0)
	v_mfma_f32_32x32x16_bf16 v[80:95], v[210:213], v[112:115], v[80:95]
	v_lshlrev_b32_e32 v2, 2, v2
	s_nop 10
	v_max3_f32 v0, v0, v80, v81
	v_max3_f32 v0, v0, v82, v83
	v_max3_f32 v0, v0, v84, v85
	v_max3_f32 v0, v0, v86, v87
	v_max3_f32 v0, v0, v88, v89
	v_max3_f32 v0, v0, v90, v91
	v_max3_f32 v0, v0, v92, v93
	v_max3_f32 v0, v0, v94, v95
	v_mov_b32_e32 v2, v0
	s_nop 1
	v_permlane32_swap_b32_e32 v2, v0
	s_nop 1
	v_add_u32_e32 v224, 0x5000, v194
	v_add_u32_e32 v225, 0x6000, v194
	v_add_u32_e32 v226, 0x7000, v194
	v_add_u32_e32 v227, 0x8000, v194
	ds_read2_b64 v[196:199], v224 offset0:128 offset1:130
	ds_read2_b64 v[202:205], v225 offset0:160 offset1:162
	ds_read2_b64 v[206:209], v226 offset0:192 offset1:194
	ds_read2_b64 v[210:213], v227 offset0:224 offset1:226
	ds_read2_b64 v[220:223], v224 offset0:132 offset1:134
	v_max3_f32 v0, v195, v0, v2
	v_sub_f32 v4, v97, v0
	v_sub_f32 v3, v96, v0
	v_sub_f32 v5, v100, v0
	v_sub_f32_e32 v2, v195, v0
	v_exp_f32_e32 v8, v4
	v_sub_f32 v4, v98, v0
	v_exp_f32_e32 v3, v3
	v_exp_f32_e32 v9, v4
	v_sub_f32 v4, v99, v0
	v_exp_f32_e32 v11, v5
	v_exp_f32_e32 v10, v4
	v_add_f32 v4, v1, v3
	v_sub_f32 v5, v101, v0
	v_exp_f32_e32 v2, v2
	v_add_f32 v4, v4, v8
	v_exp_f32_e32 v12, v5
	v_add_f32 v4, v4, v9
	v_sub_f32 v5, v102, v0
	v_cvt_pk_bf16_f32 v8, v3, v8
	v_add_f32 v4, v4, v10
	v_exp_f32_e32 v13, v5
	v_add_f32 v4, v4, v11
	v_sub_f32 v5, v103, v0
	v_add_f32 v4, v4, v12
	v_exp_f32_e32 v14, v5
	v_add_f32 v4, v4, v13
	v_cvt_pk_bf16_f32 v9, v9, v10
	v_add_f32 v96, v4, v14
	v_sub_f32 v4, v104, v0
	v_exp_f32_e32 v97, v4
	v_sub_f32 v4, v105, v0
	v_cvt_pk_bf16_f32 v10, v11, v12
	v_exp_f32_e32 v98, v4
	v_sub_f32 v4, v106, v0
	v_cvt_pk_bf16_f32 v11, v13, v14
	v_exp_f32_e32 v99, v4
	v_sub_f32 v4, v107, v0
	v_exp_f32_e32 v100, v4
	v_sub_f32 v4, v108, v0
	v_pk_mul_f32 v[64:65], v[64:65], v[2:3] op_sel_hi:[1,0]
	v_pk_mul_f32 v[66:67], v[66:67], v[2:3] op_sel_hi:[1,0]
	v_pk_mul_f32 v[68:69], v[68:69], v[2:3] op_sel_hi:[1,0]
	s_nop 0
	v_exp_f32_e32 v101, v4
	v_sub_f32 v4, v109, v0
	v_pk_mul_f32 v[70:71], v[70:71], v[2:3] op_sel_hi:[1,0]
	v_pk_mul_f32 v[72:73], v[72:73], v[2:3] op_sel_hi:[1,0]
	s_nop 0
	v_exp_f32_e32 v102, v4
	v_sub_f32 v4, v110, v0
	v_pk_mul_f32 v[74:75], v[74:75], v[2:3] op_sel_hi:[1,0]
	v_pk_mul_f32 v[76:77], v[76:77], v[2:3] op_sel_hi:[1,0]
	v_pk_mul_f32 v[78:79], v[78:79], v[2:3] op_sel_hi:[1,0]
	s_nop 0
	v_exp_f32_e32 v103, v4
	s_waitcnt lgkmcnt(4)
	v_mfma_f32_32x32x16_bf16 v[64:79], v[196:199], v[8:11], v[64:79]
	ds_read2_b64 v[196:199], v225 offset0:164 offset1:166
	v_pk_mul_f32 v[48:49], v[48:49], v[2:3] op_sel_hi:[1,0]
	v_pk_mul_f32 v[50:51], v[50:51], v[2:3] op_sel_hi:[1,0]
	v_pk_mul_f32 v[52:53], v[52:53], v[2:3] op_sel_hi:[1,0]
	v_pk_mul_f32 v[54:55], v[54:55], v[2:3] op_sel_hi:[1,0]
	v_pk_mul_f32 v[56:57], v[56:57], v[2:3] op_sel_hi:[1,0]
	v_pk_mul_f32 v[58:59], v[58:59], v[2:3] op_sel_hi:[1,0]
	v_pk_mul_f32 v[60:61], v[60:61], v[2:3] op_sel_hi:[1,0]
	v_pk_mul_f32 v[62:63], v[62:63], v[2:3] op_sel_hi:[1,0]
	s_waitcnt lgkmcnt(4)
	v_mfma_f32_32x32x16_bf16 v[48:63], v[202:205], v[8:11], v[48:63]
	ds_read2_b64 v[202:205], v226 offset0:196 offset1:198
	v_pk_mul_f32 v[32:33], v[32:33], v[2:3] op_sel_hi:[1,0]
	v_pk_mul_f32 v[34:35], v[34:35], v[2:3] op_sel_hi:[1,0]
	v_pk_mul_f32 v[36:37], v[36:37], v[2:3] op_sel_hi:[1,0]
	v_pk_mul_f32 v[38:39], v[38:39], v[2:3] op_sel_hi:[1,0]
	v_pk_mul_f32 v[40:41], v[40:41], v[2:3] op_sel_hi:[1,0]
	v_pk_mul_f32 v[42:43], v[42:43], v[2:3] op_sel_hi:[1,0]
	v_pk_mul_f32 v[44:45], v[44:45], v[2:3] op_sel_hi:[1,0]
	v_pk_mul_f32 v[46:47], v[46:47], v[2:3] op_sel_hi:[1,0]
	v_pk_mul_f32 v[16:17], v[16:17], v[2:3] op_sel_hi:[1,0]
	v_pk_mul_f32 v[18:19], v[18:19], v[2:3] op_sel_hi:[1,0]
	v_pk_mul_f32 v[20:21], v[20:21], v[2:3] op_sel_hi:[1,0]
	s_waitcnt lgkmcnt(4)
	v_mfma_f32_32x32x16_bf16 v[32:47], v[206:209], v[8:11], v[32:47]
	ds_read2_b64 v[206:209], v227 offset0:228 offset1:230
	v_pk_mul_f32 v[22:23], v[22:23], v[2:3] op_sel_hi:[1,0]
	v_pk_mul_f32 v[24:25], v[24:25], v[2:3] op_sel_hi:[1,0]
	v_pk_mul_f32 v[26:27], v[26:27], v[2:3] op_sel_hi:[1,0]
	v_pk_mul_f32 v[28:29], v[28:29], v[2:3] op_sel_hi:[1,0]
	v_pk_mul_f32 v[30:31], v[30:31], v[2:3] op_sel_hi:[1,0]
	v_mov_b32_e32 v195, v0
	s_waitcnt lgkmcnt(4)
	v_mfma_f32_32x32x16_bf16 v[16:31], v[210:213], v[8:11], v[16:31]
	ds_read2_b64 v[210:213], v224 offset0:136 offset1:138
	v_sub_f32 v8, v111, v0
	v_cvt_pk_bf16_f32 v9, v99, v100
	v_exp_f32_e32 v107, v8
	v_cvt_pk_bf16_f32 v8, v97, v98
	v_cvt_pk_bf16_f32 v10, v101, v102
	v_cvt_pk_bf16_f32 v11, v103, v107
	s_nop 0
	s_waitcnt lgkmcnt(4)
	v_mfma_f32_32x32x16_bf16 v[64:79], v[220:223], v[8:11], v[64:79]
	ds_read2_b64 v[220:223], v225 offset0:168 offset1:170
	v_add_f32 v4, v96, v97
	s_nop 0
	v_add_f32 v4, v4, v98
	s_nop 0
	v_add_f32 v4, v4, v99
	s_nop 0
	v_add_f32 v96, v4, v100
	v_sub_f32 v4, v80, v0
	s_waitcnt lgkmcnt(4)
	v_mfma_f32_32x32x16_bf16 v[48:63], v[196:199], v[8:11], v[48:63]
	ds_read2_b64 v[196:199], v226 offset0:200 offset1:202
	v_exp_f32_e32 v80, v4
	v_sub_f32 v12, v81, v0
	s_nop 0
	v_exp_f32_e32 v81, v12
	v_sub_f32 v12, v82, v0
	s_nop 0
	v_exp_f32_e32 v82, v12
	v_sub_f32 v12, v83, v0
	s_waitcnt lgkmcnt(4)
	v_mfma_f32_32x32x16_bf16 v[32:47], v[202:205], v[8:11], v[32:47]
	ds_read2_b64 v[202:205], v227 offset0:232 offset1:234
	v_exp_f32_e32 v83, v12
	v_sub_f32 v4, v84, v0
	s_nop 0
	v_exp_f32_e32 v84, v4
	v_sub_f32 v4, v85, v0
	s_nop 0
	v_exp_f32_e32 v85, v4
	v_sub_f32 v4, v86, v0
	s_waitcnt lgkmcnt(4)
	v_mfma_f32_32x32x16_bf16 v[16:31], v[206:209], v[8:11], v[16:31]
	ds_read2_b64 v[206:209], v224 offset0:140 offset1:142
	v_exp_f32_e32 v86, v4
	v_sub_f32 v8, v87, v0
	v_exp_f32_e32 v87, v8
	v_cvt_pk_bf16_f32 v8, v80, v81
	v_cvt_pk_bf16_f32 v9, v82, v83
	v_cvt_pk_bf16_f32 v10, v84, v85
	v_cvt_pk_bf16_f32 v11, v86, v87
	s_nop 0
	s_waitcnt lgkmcnt(4)
	v_mfma_f32_32x32x16_bf16 v[64:79], v[210:213], v[8:11], v[64:79]
	ds_read2_b64 v[210:213], v225 offset0:172 offset1:174
	v_add_f32 v4, v96, v101
	s_nop 0
	v_add_f32 v4, v4, v102
	s_nop 0
	v_add_f32 v4, v4, v103
	s_nop 0
	v_add_f32 v96, v4, v107
	v_sub_f32 v4, v88, v0
	s_waitcnt lgkmcnt(4)
	v_mfma_f32_32x32x16_bf16 v[48:63], v[220:223], v[8:11], v[48:63]
	ds_read2_b64 v[220:223], v226 offset0:204 offset1:206
	v_exp_f32_e32 v88, v4
	v_sub_f32 v12, v89, v0
	s_nop 0
	v_exp_f32_e32 v89, v12
	v_sub_f32 v12, v90, v0
	s_nop 0
	v_exp_f32_e32 v90, v12
	v_sub_f32 v12, v91, v0
	s_waitcnt lgkmcnt(4)
	v_mfma_f32_32x32x16_bf16 v[32:47], v[196:199], v[8:11], v[32:47]
	ds_read2_b64 v[196:199], v227 offset0:236 offset1:238
	v_exp_f32_e32 v91, v12
	v_sub_f32 v4, v92, v0
	s_nop 0
	v_exp_f32_e32 v92, v4
	v_sub_f32 v4, v93, v0
	s_nop 0
	v_exp_f32_e32 v93, v4
	v_sub_f32 v4, v94, v0
	s_waitcnt lgkmcnt(4)
	v_mfma_f32_32x32x16_bf16 v[16:31], v[202:205], v[8:11], v[16:31]
	v_exp_f32_e32 v94, v4
	v_sub_f32 v8, v95, v0
	v_cvt_pk_bf16_f32 v9, v90, v91
	v_exp_f32_e32 v95, v8
	v_cvt_pk_bf16_f32 v8, v88, v89
	v_cvt_pk_bf16_f32 v10, v92, v93
	v_add_f32 v3, v96, v80
	v_cvt_pk_bf16_f32 v11, v94, v95
	v_add_f32 v3, v3, v81
	s_nop 0
	v_add_f32 v3, v3, v82
	s_waitcnt lgkmcnt(3)
	v_mfma_f32_32x32x16_bf16 v[64:79], v[206:209], v[8:11], v[64:79]
	v_add_f32 v3, v3, v83
	s_nop 0
	v_add_f32 v3, v3, v84
	s_nop 0
	v_add_f32 v3, v3, v85
	s_waitcnt lgkmcnt(2)
	v_mfma_f32_32x32x16_bf16 v[48:63], v[210:213], v[8:11], v[48:63]
	v_add_f32 v3, v3, v86
	s_nop 0
	v_add_f32 v3, v3, v87
	s_nop 0
	v_add_f32 v3, v3, v88
	s_nop 0
	v_add_f32 v3, v3, v89
	s_waitcnt lgkmcnt(1)
	v_mfma_f32_32x32x16_bf16 v[32:47], v[220:223], v[8:11], v[32:47]
	v_add_f32 v3, v3, v90
	s_nop 0
	v_add_f32 v3, v3, v91
	s_nop 0
	v_add_f32 v3, v3, v92
	s_nop 0
	v_add_f32 v3, v3, v93
	s_waitcnt lgkmcnt(0)
	v_mfma_f32_32x32x16_bf16 v[16:31], v[196:199], v[8:11], v[16:31]
	v_add_f32 v3, v3, v94
	s_nop 0
	v_add_f32 v3, v3, v95
	s_nop 0
	v_fmac_f32_e32 v3, v184, v2
	v_mov_b32_e32 v184, v3
	s_branch .LBB0_555
